# adds: first tile barrier moved behind setup, windowed exchange reads, queue pop by idle wave 4, NA K-fragment batch + alternating priority
# speedup vs baseline: 1.0164x; 1.0013x over previous
.LBB0_231:
	s_ashr_i32 s10, s83, 8
	s_lshl_b32 s8, s10, 6
	s_bfe_u32 s3, s33, 0x40002
	s_ashr_i32 s9, s8, 31
	s_lshl_b32 s6, s3, 2
	s_bfe_u32 s85, s83, 0x40004
	s_lshl_b64 s[8:9], s[8:9], 2
	s_add_u32 s7, s4, s8
	s_addc_u32 s9, s5, s9
	s_lshl_b32 s8, s85, 3
	s_add_u32 s8, s7, s8
	s_addc_u32 s9, s9, 0
	s_add_u32 s74, s8, 0x1080
	s_addc_u32 s75, s9, 0
	s_lshl_b32 s7, s83, 2
	global_load_dword v0, v212, s[8:9] offset:128 sc1
	global_load_dword v2, v231, s[74:75] offset:4 sc1
	s_and_b32 s9, s7, 60
	v_sub_u32_e64 v1, s9, 1 clamp
	v_readlane_b32 s7, v254, 21
	v_readfirstlane_b32 s11, v1
	s_add_i32 s8, s9, s7
	s_max_u32 s7, s9, 4
	s_min_u32 s11, s11, 56
	s_sub_i32 s7, s11, s7
	s_ashr_i32 s11, s10, 31
	s_lshl_b64 s[74:75], s[10:11], 12
	s_lshl_b64 s[10:11], s[10:11], 23
	v_readlane_b32 s12, v252, 10
	s_add_u32 s76, s12, s10
	v_readlane_b32 s12, v252, 11
	s_addc_u32 s77, s12, s11
	s_lshl_b32 s78, s8, 6
	s_add_u32 s74, s74, s78
	s_addc_u32 s75, s75, 0
	v_mov_b32_e32 v149, s75
	v_or_b32_e32 v148, s74, v140
	v_readlane_b32 s74, v255, 12
	s_lshl_b32 s0, s85, 7
	s_add_i32 s95, s7, 11
	v_lshlrev_b64 v[4:5], 11, v[148:149]
	v_readlane_b32 s75, v255, 13
	v_sub_u32_e64 v65, s9, 4 clamp
	s_add_u32 s9, s87, s10
	v_readlane_b32 s10, v252, 9
	v_lshl_add_u64 v[4:5], s[74:75], 0, v[4:5]
	s_addc_u32 s11, s10, s11
	v_lshl_add_u64 v[4:5], v[4:5], 0, s[0:1]
	v_lshlrev_b32_e32 v230, 1, v142
	s_add_u32 s10, s9, s0
	v_lshl_add_u64 v[4:5], v[4:5], 0, v[230:231]
	s_addc_u32 s11, s11, 0
	s_barrier
	global_load_dwordx4 v[98:101], v[4:5], off
	v_lshl_add_u64 v[6:7], v[4:5], 0, 32
	s_mov_b64 s[74:75], 0x60
	s_add_u32 s9, s76, s0
	v_mov_b32_e32 v147, v231
	global_load_dwordx4 v[102:105], v[6:7], off
	v_lshl_add_u64 v[6:7], v[4:5], 0, 64
	v_lshl_add_u64 v[4:5], v[4:5], 0, s[74:75]
	s_addc_u32 s74, s77, 0
	v_lshl_add_u64 v[150:151], s[10:11], 0, v[146:147]
	v_readlane_b32 s10, v254, 61
	s_add_u32 s10, s9, s10
	s_addc_u32 s11, s74, 0
	s_min_i32 s9, s95, 0
	v_add_u32_e32 v1, s9, v65
	global_load_dwordx4 v[106:109], v[6:7], off
	v_lshlrev_b32_e32 v1, 6, v1
	global_load_dwordx4 v[110:113], v[4:5], off
	v_add_u32_e32 v4, v1, v141
	v_ashrrev_i32_e32 v5, 31, v4
	v_or_b32_e32 v6, v1, v145
	v_lshlrev_b32_e32 v230, 1, v144
	v_lshlrev_b64 v[4:5], 11, v[4:5]
	v_ashrrev_i32_e32 v7, 31, v6
	v_lshl_add_u64 v[152:153], s[10:11], 0, v[230:231]
	v_lshl_add_u64 v[4:5], v[150:151], 0, v[4:5]
	v_lshlrev_b64 v[6:7], 11, v[6:7]
	v_readlane_b32 s10, v252, 26
	s_mov_b32 s9, m0
	s_mov_b32 m0, s10
	s_nop 0
	global_load_lds_dwordx4 v[4:5], off
	s_mov_b32 m0, s9
	v_lshl_add_u64 v[6:7], v[152:153], 0, v[6:7]
	v_readlane_b32 s10, v252, 19
	s_mov_b32 s9, m0
	s_mov_b32 m0, s10
	s_nop 0
	global_load_lds_dwordx4 v[6:7], off
	s_mov_b32 m0, s9
	s_min_i32 s9, s95, 1
	v_add_u32_e32 v1, s9, v65
	v_lshlrev_b32_e32 v1, 6, v1
	v_add_u32_e32 v4, v1, v141
	v_ashrrev_i32_e32 v5, 31, v4
	v_or_b32_e32 v6, v1, v145
	v_lshlrev_b64 v[4:5], 11, v[4:5]
	v_ashrrev_i32_e32 v7, 31, v6
	v_lshl_add_u64 v[4:5], v[150:151], 0, v[4:5]
	v_lshlrev_b64 v[6:7], 11, v[6:7]
	v_readlane_b32 s10, v252, 20
	s_mov_b32 s9, m0
	s_mov_b32 m0, s10
	s_nop 0
	global_load_lds_dwordx4 v[4:5], off
	s_mov_b32 m0, s9
	v_lshl_add_u64 v[6:7], v[152:153], 0, v[6:7]
	v_readlane_b32 s10, v252, 21
	s_mov_b32 s9, m0
	s_mov_b32 m0, s10
	s_nop 0
	global_load_lds_dwordx4 v[6:7], off
	s_mov_b32 m0, s9
	s_min_i32 s9, s95, 2
	v_add_u32_e32 v1, s9, v65
	v_lshlrev_b32_e32 v1, 6, v1
	v_add_u32_e32 v4, v1, v141
	v_ashrrev_i32_e32 v5, 31, v4
	v_or_b32_e32 v6, v1, v145
	v_lshlrev_b64 v[4:5], 11, v[4:5]
	v_ashrrev_i32_e32 v7, 31, v6
	v_lshl_add_u64 v[4:5], v[150:151], 0, v[4:5]
	v_lshlrev_b64 v[6:7], 11, v[6:7]
	v_readlane_b32 s10, v252, 22
	s_mov_b32 s9, m0
	s_mov_b32 m0, s10
	s_nop 0
	global_load_lds_dwordx4 v[4:5], off
	s_mov_b32 m0, s9
	v_lshl_add_u64 v[6:7], v[152:153], 0, v[6:7]
	v_readlane_b32 s10, v252, 23
	s_mov_b32 s9, m0
	s_mov_b32 m0, s10
	s_nop 0
	global_load_lds_dwordx4 v[6:7], off
	s_mov_b32 m0, s9
	s_min_i32 s9, s95, 3
	v_add_u32_e32 v1, s9, v65
	v_lshlrev_b32_e32 v1, 6, v1
	v_add_u32_e32 v4, v1, v141
	v_ashrrev_i32_e32 v5, 31, v4
	v_or_b32_e32 v6, v1, v145
	v_lshlrev_b64 v[4:5], 11, v[4:5]
	v_ashrrev_i32_e32 v7, 31, v6
	v_lshl_add_u64 v[4:5], v[150:151], 0, v[4:5]
	v_lshlrev_b64 v[6:7], 11, v[6:7]
	v_readlane_b32 s10, v252, 24
	s_mov_b32 s9, m0
	s_mov_b32 m0, s10
	s_nop 0
	global_load_lds_dwordx4 v[4:5], off
	s_mov_b32 m0, s9
	v_lshl_add_u64 v[6:7], v[152:153], 0, v[6:7]
	v_readlane_b32 s10, v252, 25
	s_mov_b32 s9, m0
	s_mov_b32 m0, s10
	s_nop 0
	global_load_lds_dwordx4 v[6:7], off
	s_mov_b32 m0, s9
	s_min_i32 s9, s95, 4
	v_add_u32_e32 v1, s9, v65
	v_lshlrev_b32_e32 v1, 6, v1
	v_add_u32_e32 v4, v1, v141
	v_ashrrev_i32_e32 v5, 31, v4
	v_or_b32_e32 v6, v1, v145
	v_lshlrev_b64 v[4:5], 11, v[4:5]
	v_ashrrev_i32_e32 v7, 31, v6
	v_lshl_add_u64 v[4:5], v[150:151], 0, v[4:5]
	v_lshlrev_b64 v[6:7], 11, v[6:7]
	v_readlane_b32 s10, v252, 48
	s_mov_b32 s9, m0
	s_mov_b32 m0, s10
	s_nop 0
	global_load_lds_dwordx4 v[4:5], off
	s_mov_b32 m0, s9
	v_lshl_add_u64 v[6:7], v[152:153], 0, v[6:7]
	v_readlane_b32 s10, v252, 27
	s_mov_b32 s9, m0
	s_mov_b32 m0, s10
	s_nop 0
	global_load_lds_dwordx4 v[6:7], off
	s_mov_b32 m0, s9
	s_waitcnt vmcnt(10)
	v_readlane_b32 s10, v252, 28
	v_and_b32_e32 v3, 0xffff0000, v98
	v_lshlrev_b32_e32 v1, 16, v98
	v_mul_f32_e32 v3, v3, v3
	v_fmac_f32_e32 v3, v1, v1
	v_lshlrev_b32_e32 v1, 16, v99
	v_fmac_f32_e32 v3, v1, v1
	v_and_b32_e32 v1, 0xffff0000, v99
	v_fmac_f32_e32 v3, v1, v1
	v_lshlrev_b32_e32 v1, 16, v100
	v_fmac_f32_e32 v3, v1, v1
	v_and_b32_e32 v1, 0xffff0000, v100
	v_fmac_f32_e32 v3, v1, v1
	v_lshlrev_b32_e32 v1, 16, v101
	v_fmac_f32_e32 v3, v1, v1
	v_and_b32_e32 v1, 0xffff0000, v101
	v_fmac_f32_e32 v3, v1, v1
	v_lshlrev_b32_e32 v1, 16, v102
	v_fmac_f32_e32 v3, v1, v1
	v_and_b32_e32 v1, 0xffff0000, v102
	v_fmac_f32_e32 v3, v1, v1
	v_lshlrev_b32_e32 v1, 16, v103
	v_fmac_f32_e32 v3, v1, v1
	v_and_b32_e32 v1, 0xffff0000, v103
	v_fmac_f32_e32 v3, v1, v1
	v_lshlrev_b32_e32 v1, 16, v104
	v_fmac_f32_e32 v3, v1, v1
	v_and_b32_e32 v1, 0xffff0000, v104
	v_fmac_f32_e32 v3, v1, v1
	v_lshlrev_b32_e32 v1, 16, v105
	v_fmac_f32_e32 v3, v1, v1
	v_and_b32_e32 v1, 0xffff0000, v105
	v_fmac_f32_e32 v3, v1, v1
	v_lshlrev_b32_e32 v1, 16, v106
	v_fmac_f32_e32 v3, v1, v1
	v_and_b32_e32 v1, 0xffff0000, v106
	v_fmac_f32_e32 v3, v1, v1
	v_lshlrev_b32_e32 v1, 16, v107
	v_fmac_f32_e32 v3, v1, v1
	v_and_b32_e32 v1, 0xffff0000, v107
	v_and_b32_e32 v5, 0xffff0000, v108
	v_lshlrev_b32_e32 v4, 16, v108
	v_fmac_f32_e32 v3, v1, v1
	v_pk_mul_f32 v[4:5], v[4:5], v[4:5]
	v_sub_u32_e64 v8, s6, 1 clamp
	v_add_f32_e32 v1, v4, v3
	v_add_f32_e32 v1, v5, v1
	v_and_b32_e32 v5, 0xffff0000, v109
	v_lshlrev_b32_e32 v4, 16, v109
	v_pk_mul_f32 v[4:5], v[4:5], v[4:5]
	v_mbcnt_lo_u32_b32 v3, -1, 0
	v_mbcnt_hi_u32_b32 v3, -1, v3
	v_readlane_b32 s11, v252, 29
	v_add_f32_e32 v1, v4, v1
	v_add_f32_e32 v1, v5, v1
	v_and_b32_e32 v5, 0xffff0000, v110
	v_lshlrev_b32_e32 v4, 16, v110
	v_pk_mul_f32 v[4:5], v[4:5], v[4:5]
	v_lshlrev_b32_e32 v3, 2, v3
	v_add_f32_e32 v1, v4, v1
	v_add_f32_e32 v1, v5, v1
	v_and_b32_e32 v5, 0xffff0000, v111
	v_lshlrev_b32_e32 v4, 16, v111
	v_pk_mul_f32 v[4:5], v[4:5], v[4:5]
	v_xor_b32_e32 v3, 0x80, v3
	v_add_f32_e32 v1, v4, v1
	v_add_f32_e32 v1, v5, v1
	v_and_b32_e32 v5, 0xffff0000, v112
	v_lshlrev_b32_e32 v4, 16, v112
	v_pk_mul_f32 v[4:5], v[4:5], v[4:5]
	s_andn2_b64 vcc, exec, s[10:11]
	v_add_f32_e32 v1, v4, v1
	v_add_f32_e32 v1, v5, v1
	v_and_b32_e32 v5, 0xffff0000, v113
	v_lshlrev_b32_e32 v4, 16, v113
	v_pk_mul_f32 v[4:5], v[4:5], v[4:5]
	v_readfirstlane_b32 s9, v8
	v_add_f32_e32 v1, v4, v1
	v_add_f32_e32 v1, v5, v1
	ds_bpermute_b32 v3, v3, v1
	s_mov_b32 s100, 0
	s_cbranch_vccnz .LBB0_233
	s_mov_b32 s100, 1

.LBB0_235:
	s_xor_b32 s101, s100, s8
	s_bitcmp1_b32 s101, 0
	s_cbranch_scc1 .Lna_p1
	s_setprio 0
	s_branch .Lna_p2

.Lna_p2:
	s_mul_hi_u32 s11, s8, 0x24924925
	s_sub_i32 s74, s8, s11
	s_lshr_b32 s74, s74, 1
	s_add_i32 s74, s74, s11
	s_lshr_b32 s11, s74, 2
	s_add_i32 s74, s6, s87
	s_add_i32 s76, s74, 8
	s_add_i32 s74, s87, 17
	s_min_i32 s74, s74, s95
	v_add_u32_e32 v66, s74, v65
	v_lshlrev_b32_e32 v68, 6, v66
	s_mul_i32 s11, s11, 0x1c000
	v_add_u32_e32 v66, v68, v141
	s_sub_i32 s11, s9, s11
	v_ashrrev_i32_e32 v67, 31, v66
	v_or_b32_e32 v68, v68, v145
	s_waitcnt vmcnt(8) lgkmcnt(0)
	s_barrier
	v_lshlrev_b64 v[66:67], 11, v[66:67]
	v_ashrrev_i32_e32 v69, 31, v68
	s_add_i32 s11, s11, 0
	v_lshl_add_u64 v[66:67], v[150:151], 0, v[66:67]
	v_lshlrev_b64 v[68:69], 11, v[68:69]
	s_add_i32 s74, s11, 0x14000
	s_mov_b32 s75, m0
	s_mov_b32 m0, s74
	s_nop 0
	global_load_lds_dwordx4 v[66:67], off
	s_mov_b32 m0, s75
	s_add_i32 s11, s11, 0x16000
	v_lshl_add_u64 v[68:69], v[152:153], 0, v[68:69]
	s_mov_b32 s74, m0
	s_mov_b32 m0, s11
	s_nop 0
	global_load_lds_dwordx4 v[68:69], off
	s_mov_b32 m0, s74
	s_cmp_lt_u32 s76, s81
	s_cselect_b64 s[74:75], -1, 0
	s_cmp_gt_u32 s76, s3
	s_cselect_b64 s[76:77], -1, 0
	s_or_b64 s[74:75], s[74:75], s[76:77]
	s_and_b64 vcc, exec, s[74:75]
	s_cbranch_vccnz .LBB0_249
	s_mul_hi_u32 s11, s10, 0x24924925
	s_sub_i32 s74, s10, s11
	s_lshr_b32 s74, s74, 1
	s_add_i32 s74, s74, s11
	s_lshr_b32 s11, s74, 2
	s_mul_i32 s11, s11, 0x1c000
	s_sub_i32 s11, s78, s11
	s_add_i32 s11, s11, 0
	v_add_u32_e32 v130, s11, v158
	v_add_u32_e32 v70, v130, v154
	v_add_u32_e32 v126, v130, v159
	ds_read_b128 v[174:177], v70
	ds_read_b128 v[178:181], v70 offset:4096
	v_add_u32_e32 v131, v130, v160
	ds_read_b128 v[182:185], v126
	ds_read_b128 v[186:189], v126 offset:4096
	v_add_u32_e32 v130, v130, v161
	ds_read_b128 v[190:193], v131
	ds_read_b128 v[194:197], v131 offset:4096
	ds_read_b128 v[198:201], v130
	ds_read_b128 v[202:205], v130 offset:4096
	v_readlane_b32 s76, v252, 32
	v_readlane_b32 s77, v252, 33
	v_add_u32_e32 v168, 0, v147
	s_mov_b64 s[74:75], -1
	v_add_u32_e32 v165, 0x20670, v168
	v_add_u32_e32 v164, 0x20678, v168
	v_add_u32_e32 v167, 0x20650, v168
	v_add_u32_e32 v166, 0x20658, v168
	s_and_b64 vcc, exec, s[76:77]
	s_waitcnt lgkmcnt(7)
	v_mfma_f32_32x32x16_bf16 v[82:97], v[174:177], v[98:101], v[32:47]
	s_waitcnt lgkmcnt(6)
	v_mfma_f32_32x32x16_bf16 v[66:81], v[178:181], v[98:101], v[48:63]
	s_waitcnt lgkmcnt(5)
	v_mfma_f32_32x32x16_bf16 v[82:97], v[182:185], v[102:105], v[82:97]
	s_waitcnt lgkmcnt(4)
	v_mfma_f32_32x32x16_bf16 v[66:81], v[186:189], v[102:105], v[66:81]
	s_waitcnt lgkmcnt(3)
	v_mfma_f32_32x32x16_bf16 v[82:97], v[190:193], v[106:109], v[82:97]
	s_waitcnt lgkmcnt(2)
	v_mfma_f32_32x32x16_bf16 v[66:81], v[194:197], v[106:109], v[66:81]
	s_waitcnt lgkmcnt(1)
	v_mfma_f32_32x32x16_bf16 v[82:97], v[198:201], v[110:113], v[82:97]
	s_waitcnt lgkmcnt(0)
	v_mfma_f32_32x32x16_bf16 v[66:81], v[202:205], v[110:113], v[66:81]
	s_cbranch_vccz .LBB0_238
	v_add_u32_e32 v122, 0x20690, v168
	v_add_u32_e32 v124, 0x20698, v168
	v_add_u32_e32 v126, 0x206b0, v168
	v_add_u32_e32 v128, 0x206b8, v168
	v_add_u32_e32 v132, 0x206d0, v168
	v_add_u32_e32 v136, 0x206d8, v168
	ds_read2_b32 v[122:123], v122 offset1:1
	ds_read2_b32 v[124:125], v124 offset1:1
	ds_read2_b32 v[126:127], v126 offset1:1
	ds_read2_b32 v[128:129], v128 offset1:1
	ds_read2_b32 v[130:131], v165 offset1:1
	ds_read2_b32 v[132:133], v132 offset1:1
	ds_read2_b32 v[134:135], v164 offset1:1
	ds_read2_b32 v[136:137], v136 offset1:1
	ds_read2_b32 v[170:171], v167 offset1:1
	ds_read2_b32 v[172:173], v166 offset1:1
	s_mov_b64 s[74:75], 0
	s_waitcnt lgkmcnt(1)
	v_mov_b32_e32 v163, v170
	s_waitcnt lgkmcnt(0)
	v_mov_b32_e32 v169, v172
	s_nop 0
	v_add_f32_e32 v130, v66, v130
	v_exp_f32_e32 v130, v130
	v_add_f32_e32 v131, v67, v131
	v_exp_f32_e32 v131, v131
	v_add_f32_e32 v134, v68, v134
	v_exp_f32_e32 v134, v134
	v_add_f32_e32 v135, v69, v135
	v_exp_f32_e32 v135, v135
	v_add_f32_e32 v70, v70, v122
	v_add_f32_e32 v170, 0, v130
	v_exp_f32_e32 v70, v70
	v_add_f32_e32 v71, v71, v123
	v_add_f32_e32 v170, v131, v170
	v_exp_f32_e32 v71, v71
	v_add_f32_e32 v72, v72, v124
	v_add_f32_e32 v170, v134, v170
	v_exp_f32_e32 v72, v72
	v_add_f32_e32 v73, v73, v125
	v_add_f32_e32 v170, v135, v170
	v_exp_f32_e32 v73, v73
	v_add_f32_e32 v74, v74, v126
	v_add_f32_e32 v122, v70, v170
	v_exp_f32_e32 v74, v74
	v_add_f32_e32 v75, v75, v127
	v_add_f32_e32 v122, v71, v122
	v_exp_f32_e32 v75, v75
	v_add_f32_e32 v76, v76, v128
	v_add_f32_e32 v122, v72, v122
	v_exp_f32_e32 v76, v76
	v_add_f32_e32 v77, v77, v129
	v_add_f32_e32 v122, v73, v122
	v_exp_f32_e32 v77, v77
	v_add_f32_e32 v78, v78, v132
	v_add_f32_e32 v122, v74, v122
	v_exp_f32_e32 v78, v78
	v_add_f32_e32 v79, v79, v133
	v_add_f32_e32 v122, v75, v122
	v_exp_f32_e32 v79, v79
	v_add_f32_e32 v80, v80, v136
	v_add_f32_e32 v122, v76, v122
	v_exp_f32_e32 v80, v80
	v_add_f32_e32 v81, v81, v137
	v_add_f32_e32 v122, v77, v122
	v_exp_f32_e32 v81, v81
	v_add_f32_e32 v123, v94, v163
	v_add_f32_e32 v122, v78, v122
	v_exp_f32_e32 v123, v123
	v_add_f32_e32 v124, v95, v171
	v_add_f32_e32 v122, v79, v122
	v_exp_f32_e32 v124, v124
	v_add_f32_e32 v125, v96, v169
	v_add_f32_e32 v126, v97, v173
	v_add_f32_e32 v122, v80, v122
	v_exp_f32_e32 v125, v125
	v_exp_f32_e32 v126, v126
	v_add_f32_e32 v122, v81, v122
	v_add_f32_e32 v122, v123, v122
	v_add_f32_e32 v122, v124, v122
	v_add_f32_e32 v122, v125, v122
	v_cvt_pk_bf16_f32 v132, v123, v124
	v_cvt_pk_bf16_f32 v133, v125, v126
	v_cvt_pk_bf16_f32 v124, v78, v79
	v_cvt_pk_bf16_f32 v125, v80, v81
	v_add_f32_e32 v163, v126, v122
	v_cvt_pk_bf16_f32 v127, v134, v135
	v_cvt_pk_bf16_f32 v122, v74, v75
	v_cvt_pk_bf16_f32 v123, v76, v77
	v_mov_b64_e32 v[136:137], v[124:125]
	v_cvt_pk_bf16_f32 v126, v130, v131
	v_cvt_pk_bf16_f32 v128, v70, v71
	v_cvt_pk_bf16_f32 v129, v72, v73
	v_mov_b64_e32 v[134:135], v[122:123]

.LBB0_254:
	s_and_b64 vcc, exec, s[8:9]
	s_cbranch_vccz .LBB0_354
	v_readlane_b32 s24, v255, 28
	v_readlane_b32 s8, v251, 0
	s_lshr_b32 s0, s24, 1
	v_readlane_b32 s9, v251, 1
	v_readlane_b32 s10, v251, 2
	v_readlane_b32 s11, v251, 3
	v_readlane_b32 s12, v251, 4
	v_readlane_b32 s13, v251, 5
	v_readlane_b32 s14, v251, 6
	v_readlane_b32 s15, v251, 7
	v_readlane_b32 s16, v251, 8
	v_readlane_b32 s17, v251, 9
	s_cmp_eq_u32 s24, 0
	v_readlane_b32 s18, v251, 10
	v_readlane_b32 s19, v251, 11
	v_readlane_b32 s20, v251, 12
	v_readlane_b32 s21, v251, 13
	s_mov_b64 s[8:9], s[12:13]
	s_cselect_b64 vcc, -1, 0
	s_lshl_b64 s[4:5], s[0:1], 10
	s_mov_b64 s[10:11], s[14:15]
	v_mov_b32_e32 v0, 0x3ef1014c
	s_waitcnt lgkmcnt(0)
	v_mov_b32_e32 v1, 0x3e4ccccd
	s_add_u32 s8, s10, s4
	v_cndmask_b32_e32 v0, v0, v1, vcc
	s_addc_u32 s9, s11, s5
	v_lshlrev_b32_e32 v1, 2, v157
	global_load_dword v2, v1, s[8:9]
	global_load_dword v3, v1, s[8:9] offset:256
	v_mbcnt_lo_u32_b32 v5, -1, 0
	v_mbcnt_hi_u32_b32 v5, -1, v5
	s_mov_b32 s3, 0x3fb8aa3b
	v_lshlrev_b32_e32 v5, 2, v5
	v_xor_b32_e32 v5, 4, v5
	s_mov_b32 s4, 0xc2ce8ed0
	s_mov_b32 s5, 0x42b17218
	v_mov_b32_e32 v6, 0x7f800000
	s_mov_b64 s[12:13], s[16:17]
	s_mov_b64 s[14:15], s[18:19]
	s_mov_b64 s[16:17], s[20:21]
	v_readlane_b32 s44, v252, 36
	v_readlane_b32 s10, v252, 34
	v_readlane_b32 s11, v252, 35
	v_and_b32_e32 v148, 31, v138
	v_sub_f32_e32 v151, 1.0, v0
	v_lshlrev_b32_e32 v164, 7, v148
	v_readlane_b32 s43, v252, 50
	v_readlane_b32 s45, v252, 53
	v_readlane_b32 s46, v252, 55
	v_readlane_b32 s47, v252, 38
	v_readlane_b32 s48, v252, 39
	v_readlane_b32 s49, v252, 40
	v_readlane_b32 s50, v252, 42
	v_readlane_b32 s51, v252, 41
	v_readlane_b32 s77, v252, 43
	v_readlane_b32 s78, v252, 49
	v_readlane_b32 s25, v255, 29
	v_readlane_b32 s22, v251, 14
	v_readlane_b32 s23, v251, 15
	s_waitcnt vmcnt(0)
	v_mul_f32_e32 v4, v2, v3
	ds_bpermute_b32 v4, v5, v4
	s_waitcnt lgkmcnt(0)
	v_fmac_f32_e32 v4, v2, v3
	v_mbcnt_lo_u32_b32 v2, -1, 0
	v_mbcnt_hi_u32_b32 v2, -1, v2
	v_mbcnt_lo_u32_b32 v3, -1, 0
	v_mbcnt_hi_u32_b32 v3, -1, v3
	s_nop 0
	v_lshlrev_b32_e32 v2, 2, v2
	v_xor_b32_e32 v2, 8, v2
	ds_bpermute_b32 v2, v2, v4
	v_lshlrev_b32_e32 v3, 2, v3
	v_xor_b32_e32 v3, 16, v3
	s_waitcnt lgkmcnt(0)
	v_add_f32_e32 v2, v4, v2
	ds_bpermute_b32 v3, v3, v2
	s_waitcnt lgkmcnt(0)
	v_add_f32_e32 v2, v2, v3
	v_mbcnt_lo_u32_b32 v3, -1, 0
	v_mbcnt_hi_u32_b32 v3, -1, v3
	s_nop 0
	v_lshlrev_b32_e32 v3, 2, v3
	v_xor_b32_e32 v3, 32, v3
	ds_bpermute_b32 v3, v3, v2
	s_waitcnt lgkmcnt(0)
	v_add_f32_e32 v2, v2, v3
	v_mbcnt_lo_u32_b32 v3, -1, 0
	v_mbcnt_hi_u32_b32 v3, -1, v3
	s_nop 0
	v_lshlrev_b32_e32 v3, 2, v3
	v_xor_b32_e32 v3, 64, v3
	ds_bpermute_b32 v3, v3, v2
	s_waitcnt lgkmcnt(0)
	v_add_f32_e32 v2, v2, v3
	v_mbcnt_lo_u32_b32 v3, -1, 0
	v_mbcnt_hi_u32_b32 v3, -1, v3
	s_nop 0
	v_lshlrev_b32_e32 v3, 2, v3
	v_xor_b32_e32 v3, 0x80, v3
	ds_bpermute_b32 v3, v3, v2
	s_waitcnt lgkmcnt(0)
	v_add_f32_e32 v2, v2, v3
	v_mul_f32_e32 v3, 0x3fb8aa3b, v2
	v_fma_f32 v4, v2, s3, -v3
	v_rndne_f32_e32 v5, v3
	v_fmac_f32_e32 v4, 0x32a5705f, v2
	v_sub_f32_e32 v3, v3, v5
	v_add_f32_e32 v3, v3, v4
	v_exp_f32_e32 v3, v3
	v_cvt_i32_f32_e32 v4, v5
	v_cmp_ngt_f32_e32 vcc, s4, v2
	v_ldexp_f32 v3, v3, v4
	s_nop 0
	v_cndmask_b32_e32 v3, 0, v3, vcc
	v_cmp_nlt_f32_e32 vcc, s5, v2
	s_nop 1
	v_cndmask_b32_e32 v2, v6, v3, vcc
	global_load_dword v3, v1, s[8:9] offset:512
	s_nop 0
	global_load_dword v1, v1, s[8:9] offset:768
	v_mbcnt_lo_u32_b32 v5, -1, 0
	v_mbcnt_hi_u32_b32 v5, -1, v5
	v_cmp_eq_u32_e64 s[8:9], 0, v138
	v_lshlrev_b32_e32 v5, 2, v5
	v_xor_b32_e32 v5, 4, v5
	s_waitcnt vmcnt(0)
	v_mul_f32_e32 v4, v3, v1
	ds_bpermute_b32 v4, v5, v4
	s_waitcnt lgkmcnt(0)
	v_fmac_f32_e32 v4, v3, v1
	v_mbcnt_lo_u32_b32 v1, -1, 0
	v_mbcnt_hi_u32_b32 v1, -1, v1
	v_mbcnt_lo_u32_b32 v3, -1, 0
	v_mbcnt_hi_u32_b32 v3, -1, v3
	s_nop 0
	v_lshlrev_b32_e32 v1, 2, v1
	v_xor_b32_e32 v1, 8, v1
	ds_bpermute_b32 v1, v1, v4
	v_lshlrev_b32_e32 v3, 2, v3
	v_xor_b32_e32 v3, 16, v3
	s_waitcnt lgkmcnt(0)
	v_add_f32_e32 v1, v4, v1
	ds_bpermute_b32 v3, v3, v1
	s_waitcnt lgkmcnt(0)
	v_add_f32_e32 v1, v1, v3
	v_mbcnt_lo_u32_b32 v3, -1, 0
	v_mbcnt_hi_u32_b32 v3, -1, v3
	s_nop 0
	v_lshlrev_b32_e32 v3, 2, v3
	v_xor_b32_e32 v3, 32, v3
	ds_bpermute_b32 v3, v3, v1
	s_waitcnt lgkmcnt(0)
	v_add_f32_e32 v1, v1, v3
	v_mbcnt_lo_u32_b32 v3, -1, 0
	v_mbcnt_hi_u32_b32 v3, -1, v3
	s_nop 0
	v_lshlrev_b32_e32 v3, 2, v3
	v_xor_b32_e32 v3, 64, v3
	ds_bpermute_b32 v3, v3, v1
	s_waitcnt lgkmcnt(0)
	v_add_f32_e32 v1, v1, v3
	v_mbcnt_lo_u32_b32 v3, -1, 0
	v_mbcnt_hi_u32_b32 v3, -1, v3
	s_nop 0
	v_lshlrev_b32_e32 v3, 2, v3
	v_xor_b32_e32 v3, 0x80, v3
	ds_bpermute_b32 v3, v3, v1
	s_waitcnt lgkmcnt(0)
	v_add_f32_e32 v1, v1, v3
	v_mul_f32_e32 v3, 0x3fb8aa3b, v1
	v_fma_f32 v4, v1, s3, -v3
	v_rndne_f32_e32 v5, v3
	v_fmac_f32_e32 v4, 0x32a5705f, v1
	v_sub_f32_e32 v3, v3, v5
	v_add_f32_e32 v3, v3, v4
	v_exp_f32_e32 v3, v3
	v_cvt_i32_f32_e32 v4, v5
	v_cmp_ngt_f32_e32 vcc, s4, v1
	v_readlane_b32 s3, v251, 50
	v_lshrrev_b32_e32 v5, 2, v138
	v_ldexp_f32 v3, v3, v4
	v_cndmask_b32_e32 v3, 0, v3, vcc
	v_cmp_nlt_f32_e32 vcc, s5, v1
	s_lshl_b64 s[4:5], s[0:1], 9
	s_add_u32 s14, s12, s4
	s_addc_u32 s15, s13, s5
	s_lshl_b32 s0, s24, 8
	s_lshl_b64 s[4:5], s[0:1], 2
	s_add_u32 s4, s3, s4
	v_readlane_b32 s3, v251, 51
	s_addc_u32 s5, s3, s5
	s_lshl_b32 s3, s24, 2
	s_add_i32 s6, s3, s44
	s_lshl_b32 s6, s6, 6
	v_cndmask_b32_e32 v1, v6, v3, vcc
	s_ashr_i32 s7, s6, 31
	v_sub_f32_e32 v1, v2, v1
	v_lshlrev_b32_e32 v2, 3, v157
	s_lshl_b64 s[6:7], s[6:7], 2
	v_and_b32_e32 v150, 24, v2
	v_lshrrev_b32_e32 v2, 3, v157
	s_add_u32 s16, s10, s6
	v_readlane_b32 s6, v252, 37
	v_xor_b32_e32 v4, v2, v157
	s_addc_u32 s17, s11, s7
	s_add_i32 s3, s3, s6
	v_lshrrev_b32_e32 v3, 5, v157
	v_lshlrev_b32_e32 v4, 3, v4
	s_lshl_b32 s6, s3, 6
	v_and_b32_e32 v152, 56, v4
	v_lshlrev_b32_e32 v4, 2, v3
	s_ashr_i32 s7, s6, 31
	v_add_f32_e32 v149, v0, v1
	v_lshlrev_b32_e32 v0, 3, v3
	v_lshrrev_b32_e32 v1, 2, v157
	v_sub_u32_e32 v153, v148, v4
	v_and_or_b32 v4, v5, 3, v4
	v_lshlrev_b32_e32 v5, 1, v157
	v_bitop3_b32 v3, v3, v138, 7 bitop3:0x78
	s_lshl_b64 s[6:7], s[6:7], 2
	v_readlane_b32 s3, v252, 16
	v_lshlrev_b32_e32 v4, 6, v4
	v_and_b32_e32 v5, 32, v5
	v_lshlrev_b32_e32 v163, 4, v3
	s_add_u32 s18, s10, s6
	v_or_b32_e32 v168, s3, v1
	v_readlane_b32 s3, v252, 18
	v_or3_b32 v162, v5, v4, v150
	v_xor_b32_e32 v165, 32, v163
	v_xor_b32_e32 v166, 64, v163
	v_xor_b32_e32 v167, 0x60, v163
	s_addc_u32 s19, s11, s7
	v_or_b32_e32 v169, s3, v2
	v_lshlrev_b32_e32 v154, 1, v0
	v_cmp_gt_u32_e32 vcc, 0x80, v138
	s_and_saveexec_b64 s[10:11], vcc
	v_lshlrev_b32_e32 v0, 2, v138
	global_load_dword v1, v0, s[14:15]
	v_add_u32_e32 v0, 0x20340, v0
	s_waitcnt vmcnt(0)
	ds_write_b32 v0, v1
	s_waitcnt lgkmcnt(0)
	s_or_b64 exec, exec, s[10:11]
	s_cmp_eq_u32 s95, 0x100
	s_cbranch_scc0 .Lda_popskip_a
	s_mov_b64 exec, 1
	global_atomic_add v0, v231, v214, s[16:17] sc0
	s_waitcnt vmcnt(0)
	s_movk_i32 s3, 0x7f
	v_cmp_lt_u32_e32 vcc, s3, v0
	s_and_saveexec_b64 s[12:13], vcc
	s_cbranch_execz .Lda_popw_a
	global_atomic_add v0, v231, v214, s[18:19] sc0
	s_waitcnt vmcnt(0)
	v_or_b32_e32 v1, 0x100, v0
	v_cmp_gt_u32_e32 vcc, s58, v0
	s_nop 1
	v_cndmask_b32_e32 v0, v218, v1, vcc
.Lda_popw_a:
	s_or_b64 exec, exec, s[12:13]
	v_mov_b32_e32 v1, s59
	ds_write_b32 v1, v0
	s_waitcnt lgkmcnt(0)
	s_mov_b64 exec, -1
.Lda_popskip_a:
	s_branch .LBB0_258

.LBB0_258:
	s_barrier
	s_branch .LBB0_266
	s_mov_b64 s[20:21], exec
	v_mbcnt_lo_u32_b32 v0, s20, 0
	v_mbcnt_hi_u32_b32 v0, s21, v0
	v_cmp_eq_u32_e32 vcc, 0, v0
	s_and_saveexec_b64 s[12:13], vcc
	s_cbranch_execz .LBB0_261
	s_bcnt1_i32_b64 s3, s[20:21]
	v_mov_b32_e32 v1, s3
	global_atomic_add v1, v231, v1, s[16:17] sc0

.LBB0_282:
	s_add_i32 s10, s28, 1
	v_cvt_f32_i32_e32 v2, s10
	s_mov_b32 s10, 0x42fc0000
	s_mov_b32 s12, 0x43020000
	v_cmp_lt_f32_e32 vcc, s10, v2
	s_and_b64 s[10:11], vcc, exec
	s_cselect_b32 s10, 0xffffffc0, 0
	v_cndmask_b32_e32 v3, 0, v219, vcc
	v_sub_f32_e32 v2, v3, v2
	v_exp_f32_e32 v2, v2
	s_lshl_b32 s33, s29, 1
	v_ldexp_f32 v2, v2, s10
	v_mul_f32_e32 v156, 0x3fb8aa3b, v2
	v_div_scale_f32 v2, s[10:11], v156, v156, s12
	v_rcp_f32_e32 v3, v2
	s_sub_i32 s10, s3, 63
	v_fma_f32 v4, -v2, v3, 1.0
	v_fmac_f32_e32 v3, v4, v3
	v_div_scale_f32 v4, vcc, s12, v156, s12
	v_mul_f32_e32 v5, v4, v3
	v_fma_f32 v6, -v2, v5, v4
	v_fmac_f32_e32 v5, v6, v3
	v_fma_f32 v2, -v2, v5, v4
	v_div_fmas_f32 v2, v2, v3, v5
	v_cvt_f32_i32_e32 v3, s10
	s_or_b32 s10, s3, 0x7f
	v_div_fixup_f32 v2, v2, v156, s12
	v_cvt_f32_i32_e32 v4, s10
	v_sub_f32_e32 v3, v3, v2
	v_mul_f32_e32 v3, 0x3c800000, v3
	v_ceil_f32_e32 v3, v3
	v_cvt_i32_f32_e32 v3, v3
	v_add_f32_e32 v2, v2, v4
	v_mul_f32_e32 v2, 0x3c800000, v2
	v_floor_f32_e32 v2, v2
	v_cvt_i32_f32_e32 v2, v2
	v_readfirstlane_b32 s10, v3
	s_min_i32 s11, s33, s10
	s_cmp_gt_i32 s10, -1
	s_cselect_b32 s10, s11, 0
	s_or_b32 s11, s33, 1
	v_readfirstlane_b32 s12, v2
	s_cmp_lt_i32 s33, s12
	s_cselect_b32 s11, s12, s11
	s_cmp_lt_i32 s12, 64
	s_cselect_b32 s37, s11, 63
	s_sub_i32 s36, s33, s10
	s_not_b32 s10, s33
	s_add_i32 s37, s37, s10
	s_add_i32 s34, s37, s36
	s_add_i32 s35, s34, 2
	s_cmp_gt_i32 s34, 0
	s_cselect_b64 s[26:27], -1, 0
	s_cmp_lt_i32 s34, 1
	s_cbranch_scc1 .LBB0_301
	s_min_i32 s40, s36, s37
	s_cmp_lt_i32 s40, 1
	s_cselect_b64 s[10:11], -1, 0
	s_mov_b64 s[12:13], -1
	s_and_b64 vcc, exec, s[10:11]
	s_cbranch_vccz .LBB0_289
	s_lshl_b32 s12, s40, 1
	s_sub_i32 s42, 0, s12
	s_cmp_le_i32 s36, s37
	s_mov_b64 s[12:13], -1
	s_cbranch_scc0 .LBB0_286
	s_add_i32 s12, s33, s40
	s_add_i32 s12, s12, s42
	s_add_i32 s41, s12, 2
	s_mov_b64 s[12:13], 0

.LBB0_301:
	s_nop 0
	v_readlane_b32 s10, v252, 46
	s_waitcnt lgkmcnt(0)
	v_add_f32_e32 v0, v0, v1
	v_mov_b32_e32 v1, s39
	v_mov_b32_e32 v2, s7
	v_readlane_b32 s11, v252, 47
	v_readlane_b32 s40, v252, 57
	v_readlane_b32 s12, v252, 60
	v_cndmask_b32_e64 v1, v1, v2, s[10:11]
	v_mul_f32_e32 v0, v1, v0
	v_mul_f32_e32 v1, 0x4f800000, v0
	v_cmp_gt_f32_e32 vcc, s79, v0
	v_readlane_b32 s13, v252, 61
	v_mov_b32_e32 v52, 0
	v_cndmask_b32_e32 v0, v0, v1, vcc
	v_sqrt_f32_e32 v1, v0
	v_mul_f32_e32 v48, 0x41000000, v156
	v_mov_b32_e32 v4, 0
	v_mov_b32_e32 v5, 0
	v_add_u32_e32 v2, -1, v1
	v_fma_f32 v3, -v2, v1, v0
	v_cmp_ge_f32_e64 s[10:11], 0, v3
	v_add_u32_e32 v3, 1, v1
	v_mov_b32_e32 v6, 0
	v_cndmask_b32_e64 v2, v1, v2, s[10:11]
	v_fma_f32 v1, -v3, v1, v0
	v_cmp_lt_f32_e64 s[10:11], 0, v1
	v_mov_b32_e32 v7, 0
	v_mov_b32_e32 v8, 0
	v_cndmask_b32_e64 v1, v2, v3, s[10:11]
	v_mul_f32_e32 v2, 0x37800000, v1
	v_cndmask_b32_e32 v1, v1, v2, vcc
	v_cmp_class_f32_e32 vcc, v0, v215
	v_mov_b32_e32 v3, 0
	v_mov_b32_e32 v9, 0
	v_cndmask_b32_e32 v0, v1, v0, vcc
	v_fmamk_f32 v155, v0, 0x3f8147ae, v216
	v_add_u32_e32 v0, s6, v153
	s_mov_b32 s6, s1
	s_add_i32 s6, s6, 0
	s_add_i32 s7, s6, s40
	v_cvt_f32_i32_e32 v170, v0
	v_add_u32_e32 v0, s7, v164
	v_add_u32_e32 v2, v0, v163
	s_cmp_lt_i32 s35, 4
	s_cbranch_scc1 .Lda_b3_all
	s_waitcnt vmcnt(8)
	s_branch .Lda_b3

.Lda_b3:
	s_waitcnt lgkmcnt(0)
	s_barrier
	ds_read_b128 v[32:35], v2
	ds_read_b128 v[28:31], v2 offset:4096
	v_add_u32_e32 v2, v0, v165
	ds_read_b128 v[36:39], v2
	ds_read_b128 v[24:27], v2 offset:4096
	v_add_u32_e32 v2, v0, v166
	v_add_u32_e32 v0, v0, v167
	v_cvt_f32_i32_e32 v1, s3
	ds_read_b128 v[40:43], v2
	ds_read_b128 v[20:23], v2 offset:4096
	ds_read_b128 v[44:47], v0
	ds_read_b128 v[16:19], v0 offset:4096
	v_cndmask_b32_e64 v0, 0, 1, s[12:13]
	v_sub_f32_e32 v76, v170, v1
	v_cmp_ne_u32_e64 s[10:11], 1, v0
	s_andn2_b64 vcc, exec, s[12:13]
	v_mov_b32_e32 v0, 0
	v_mov_b32_e32 v1, 0
	v_mov_b32_e32 v2, 0
	v_mov_b32_e32 v10, 0
	v_mov_b32_e32 v11, 0
	v_mov_b32_e32 v12, 0
	v_mov_b32_e32 v13, 0
	v_mov_b32_e32 v14, 0
	v_mov_b32_e32 v15, 0
	s_cbranch_vccnz .LBB0_303
	v_fma_f32 v0, v156, -v76, -v155
	v_add_f32_e32 v4, v48, v0
	v_add_f32_e32 v1, v156, v0
	s_nop 0
	v_add_f32_e32 v8, v48, v4
	v_add_f32_e32 v2, v156, v1
	v_add_f32_e32 v5, v156, v4
	s_nop 0
	v_add_f32_e32 v12, v48, v8
	v_add_f32_e32 v3, v156, v2
	v_add_f32_e32 v6, v156, v5
	v_add_f32_e32 v9, v156, v8
	s_nop 0
	v_add_f32_e32 v7, v156, v6
	v_add_f32_e32 v10, v156, v9
	v_add_f32_e32 v13, v156, v12
	s_nop 0
	v_add_f32_e32 v11, v156, v10
	v_add_f32_e32 v14, v156, v13
	s_nop 0
	v_add_f32_e32 v15, v156, v14
	s_nop 0
	s_nop 1

.LBB0_352:
	v_readlane_b32 s6, v252, 46
	v_readlane_b32 s7, v252, 47
	s_andn2_b64 vcc, exec, s[6:7]
	s_waitcnt lgkmcnt(0)
	s_barrier
	s_cbranch_vccnz .Lda_pop_b
	ds_read2_b32 v[174:175], v95 offset0:114 offset1:115
	ds_read2_b32 v[176:177], v95 offset0:120 offset1:121
	ds_read2_b32 v[178:179], v95 offset0:122 offset1:123
	ds_read2_b32 v[180:181], v95 offset0:10 offset1:11
	ds_read2_b32 v[182:183], v95 offset0:8 offset1:9
	ds_read2_b32 v[184:185], v95 offset0:2 offset1:3
	ds_read2_b32 v[186:187], v95 offset1:1
	ds_read2_b32 v[188:189], v95 offset0:26 offset1:27
	ds_read2_b32 v[190:191], v95 offset0:24 offset1:25
	ds_read2_b32 v[192:193], v95 offset0:18 offset1:19
	ds_read2_b32 v[194:195], v95 offset0:16 offset1:17
	ds_read2_b32 v[196:197], v95 offset0:42 offset1:43
	ds_read2_b32 v[198:199], v95 offset0:40 offset1:41
	ds_read2_b32 v[200:201], v95 offset0:34 offset1:35
	ds_read2_b32 v[202:203], v95 offset0:32 offset1:33
	v_lshlrev_b32_e32 v68, 2, v67
	v_ashrrev_i32_e32 v69, 31, v68
	v_readlane_b32 s6, v253, 16
	s_waitcnt lgkmcnt(14)
	v_pk_fma_f32 v[58:59], v[58:59], v[66:67], v[174:175] op_sel_hi:[1,0,1] neg_lo:[0,0,1] neg_hi:[0,0,1]
	ds_read2_b32 v[174:175], v95 offset0:58 offset1:59
	s_waitcnt lgkmcnt(14)
	v_pk_fma_f32 v[64:65], v[60:61], v[66:67], v[176:177] op_sel_hi:[1,0,1] neg_lo:[0,0,1] neg_hi:[0,0,1]
	ds_read2_b32 v[176:177], v95 offset0:56 offset1:57
	s_waitcnt lgkmcnt(14)
	v_pk_fma_f32 v[60:61], v[62:63], v[66:67], v[178:179] op_sel_hi:[1,0,1] neg_lo:[0,0,1] neg_hi:[0,0,1]
	ds_read2_b32 v[178:179], v95 offset0:50 offset1:51
	v_lshlrev_b32_e32 v62, 2, v68
	v_add_u32_e32 v62, 0x20340, v62
	v_pk_mul_f32 v[98:99], v[58:59], v[58:59]
	v_pk_mul_f32 v[100:101], v[64:65], v[64:65]
	s_waitcnt lgkmcnt(14)
	v_pk_fma_f32 v[86:87], v[6:7], v[66:67], v[180:181] op_sel_hi:[1,0,1] neg_lo:[0,0,1] neg_hi:[0,0,1]
	ds_read2_b32 v[180:181], v95 offset0:48 offset1:49
	s_waitcnt lgkmcnt(14)
	v_pk_fma_f32 v[88:89], v[4:5], v[66:67], v[182:183] op_sel_hi:[1,0,1] neg_lo:[0,0,1] neg_hi:[0,0,1]
	ds_read2_b32 v[182:183], v95 offset0:74 offset1:75
	v_pk_mul_f32 v[106:107], v[88:89], v[88:89]
	v_pk_mul_f32 v[104:105], v[86:87], v[86:87]
	s_waitcnt lgkmcnt(14)
	v_pk_fma_f32 v[90:91], v[2:3], v[66:67], v[184:185] op_sel_hi:[1,0,1] neg_lo:[0,0,1] neg_hi:[0,0,1]
	ds_read2_b32 v[184:185], v95 offset0:72 offset1:73
	s_waitcnt lgkmcnt(14)
	v_pk_fma_f32 v[92:93], v[0:1], v[66:67], v[186:187] op_sel_hi:[1,0,1] neg_lo:[0,0,1] neg_hi:[0,0,1]
	ds_read2_b32 v[186:187], v95 offset0:66 offset1:67
	v_pk_mul_f32 v[110:111], v[92:93], v[92:93]
	v_pk_mul_f32 v[108:109], v[90:91], v[90:91]
	s_waitcnt lgkmcnt(14)
	v_pk_fma_f32 v[78:79], v[14:15], v[66:67], v[188:189] op_sel_hi:[1,0,1] neg_lo:[0,0,1] neg_hi:[0,0,1]
	ds_read2_b32 v[188:189], v95 offset0:64 offset1:65
	s_waitcnt lgkmcnt(14)
	v_pk_fma_f32 v[80:81], v[12:13], v[66:67], v[190:191] op_sel_hi:[1,0,1] neg_lo:[0,0,1] neg_hi:[0,0,1]
	ds_read2_b32 v[190:191], v95 offset0:90 offset1:91
	v_pk_mul_f32 v[114:115], v[80:81], v[80:81]
	v_pk_mul_f32 v[112:113], v[78:79], v[78:79]
	s_waitcnt lgkmcnt(14)
	v_pk_fma_f32 v[82:83], v[10:11], v[66:67], v[192:193] op_sel_hi:[1,0,1] neg_lo:[0,0,1] neg_hi:[0,0,1]
	ds_read2_b32 v[192:193], v95 offset0:88 offset1:89
	s_waitcnt lgkmcnt(14)
	v_pk_fma_f32 v[84:85], v[8:9], v[66:67], v[194:195] op_sel_hi:[1,0,1] neg_lo:[0,0,1] neg_hi:[0,0,1]
	ds_read2_b32 v[194:195], v95 offset0:82 offset1:83
	v_pk_mul_f32 v[118:119], v[84:85], v[84:85]
	v_pk_mul_f32 v[116:117], v[82:83], v[82:83]
	s_waitcnt lgkmcnt(14)
	v_pk_fma_f32 v[70:71], v[22:23], v[66:67], v[196:197] op_sel_hi:[1,0,1] neg_lo:[0,0,1] neg_hi:[0,0,1]
	ds_read2_b32 v[196:197], v95 offset0:80 offset1:81
	s_waitcnt lgkmcnt(14)
	v_pk_fma_f32 v[72:73], v[20:21], v[66:67], v[198:199] op_sel_hi:[1,0,1] neg_lo:[0,0,1] neg_hi:[0,0,1]
	ds_read2_b32 v[198:199], v95 offset0:106 offset1:107
	v_pk_mul_f32 v[122:123], v[72:73], v[72:73]
	v_pk_mul_f32 v[120:121], v[70:71], v[70:71]
	s_waitcnt lgkmcnt(14)
	v_pk_fma_f32 v[74:75], v[18:19], v[66:67], v[200:201] op_sel_hi:[1,0,1] neg_lo:[0,0,1] neg_hi:[0,0,1]
	ds_read2_b32 v[200:201], v95 offset0:104 offset1:105
	s_waitcnt lgkmcnt(14)
	v_pk_fma_f32 v[76:77], v[16:17], v[66:67], v[202:203] op_sel_hi:[1,0,1] neg_lo:[0,0,1] neg_hi:[0,0,1]
	ds_read2_b32 v[202:203], v95 offset0:98 offset1:99
	v_pk_mul_f32 v[126:127], v[76:77], v[76:77]
	v_pk_mul_f32 v[124:125], v[74:75], v[74:75]
	s_waitcnt lgkmcnt(14)
	v_pk_fma_f32 v[30:31], v[30:31], v[66:67], v[174:175] op_sel_hi:[1,0,1] neg_lo:[0,0,1] neg_hi:[0,0,1]
	ds_read2_b32 v[174:175], v95 offset0:96 offset1:97
	s_waitcnt lgkmcnt(14)
	v_pk_fma_f32 v[28:29], v[28:29], v[66:67], v[176:177] op_sel_hi:[1,0,1] neg_lo:[0,0,1] neg_hi:[0,0,1]
	ds_read2_b32 v[176:177], v95 offset0:112 offset1:113
	v_pk_mul_f32 v[130:131], v[28:29], v[28:29]
	v_pk_mul_f32 v[128:129], v[30:31], v[30:31]
	s_waitcnt lgkmcnt(14)
	v_pk_fma_f32 v[26:27], v[26:27], v[66:67], v[178:179] op_sel_hi:[1,0,1] neg_lo:[0,0,1] neg_hi:[0,0,1]
	s_waitcnt lgkmcnt(13)
	v_pk_fma_f32 v[68:69], v[24:25], v[66:67], v[180:181] op_sel_hi:[1,0,1] neg_lo:[0,0,1] neg_hi:[0,0,1]
	v_pk_mul_f32 v[134:135], v[68:69], v[68:69]
	v_pk_mul_f32 v[132:133], v[26:27], v[26:27]
	s_waitcnt lgkmcnt(12)
	v_pk_fma_f32 v[18:19], v[38:39], v[66:67], v[182:183] op_sel_hi:[1,0,1] neg_lo:[0,0,1] neg_hi:[0,0,1]
	s_waitcnt lgkmcnt(11)
	v_pk_fma_f32 v[20:21], v[36:37], v[66:67], v[184:185] op_sel_hi:[1,0,1] neg_lo:[0,0,1] neg_hi:[0,0,1]
	v_add_f32_e32 v36, v110, v111
	v_add_f32_e32 v36, v36, v108
	v_add_f32_e32 v36, v36, v109
	v_add_f32_e32 v36, v36, v106
	v_add_f32_e32 v36, v36, v107
	v_add_f32_e32 v36, v36, v104
	v_add_f32_e32 v36, v36, v105
	v_add_f32_e32 v36, v36, v118
	v_add_f32_e32 v36, v36, v119
	v_add_f32_e32 v36, v36, v116
	v_add_f32_e32 v36, v36, v117
	v_add_f32_e32 v36, v36, v114
	v_add_f32_e32 v36, v36, v115
	v_add_f32_e32 v36, v36, v112
	v_add_f32_e32 v36, v36, v113
	v_add_f32_e32 v36, v36, v126
	s_waitcnt lgkmcnt(10)
	v_pk_fma_f32 v[22:23], v[34:35], v[66:67], v[186:187] op_sel_hi:[1,0,1] neg_lo:[0,0,1] neg_hi:[0,0,1]
	s_waitcnt lgkmcnt(9)
	v_pk_fma_f32 v[24:25], v[32:33], v[66:67], v[188:189] op_sel_hi:[1,0,1] neg_lo:[0,0,1] neg_hi:[0,0,1]
	v_add_f32_e32 v36, v36, v127
	v_add_f32_e32 v36, v36, v124
	v_add_f32_e32 v36, v36, v125
	v_add_f32_e32 v36, v36, v122
	v_add_f32_e32 v36, v36, v123
	s_waitcnt lgkmcnt(8)
	v_pk_fma_f32 v[10:11], v[46:47], v[66:67], v[190:191] op_sel_hi:[1,0,1] neg_lo:[0,0,1] neg_hi:[0,0,1]
	s_waitcnt lgkmcnt(7)
	v_pk_fma_f32 v[12:13], v[44:45], v[66:67], v[192:193] op_sel_hi:[1,0,1] neg_lo:[0,0,1] neg_hi:[0,0,1]
	v_add_f32_e32 v36, v36, v120
	v_add_f32_e32 v36, v36, v121
	v_add_f32_e32 v36, v36, v134
	v_add_f32_e32 v36, v36, v135
	v_add_f32_e32 v36, v36, v132
	s_waitcnt lgkmcnt(6)
	v_pk_fma_f32 v[14:15], v[42:43], v[66:67], v[194:195] op_sel_hi:[1,0,1] neg_lo:[0,0,1] neg_hi:[0,0,1]
	s_waitcnt lgkmcnt(5)
	v_pk_fma_f32 v[16:17], v[40:41], v[66:67], v[196:197] op_sel_hi:[1,0,1] neg_lo:[0,0,1] neg_hi:[0,0,1]
	v_add_f32_e32 v36, v36, v133
	v_add_f32_e32 v36, v36, v130
	v_add_f32_e32 v36, v36, v131
	v_add_f32_e32 v36, v36, v128
	v_pk_mul_f32 v[32:33], v[24:25], v[24:25]
	v_add_f32_e32 v36, v36, v129
	s_waitcnt lgkmcnt(4)
	v_pk_fma_f32 v[2:3], v[54:55], v[66:67], v[198:199] op_sel_hi:[1,0,1] neg_lo:[0,0,1] neg_hi:[0,0,1]
	s_waitcnt lgkmcnt(3)
	v_pk_fma_f32 v[4:5], v[52:53], v[66:67], v[200:201] op_sel_hi:[1,0,1] neg_lo:[0,0,1] neg_hi:[0,0,1]
	s_waitcnt lgkmcnt(2)
	v_pk_fma_f32 v[6:7], v[50:51], v[66:67], v[202:203] op_sel_hi:[1,0,1] neg_lo:[0,0,1] neg_hi:[0,0,1]
	s_waitcnt lgkmcnt(1)
	v_pk_fma_f32 v[8:9], v[48:49], v[66:67], v[174:175] op_sel_hi:[1,0,1] neg_lo:[0,0,1] neg_hi:[0,0,1]
	s_waitcnt lgkmcnt(0)
	v_pk_fma_f32 v[0:1], v[56:57], v[66:67], v[176:177] op_sel_hi:[1,0,1] neg_lo:[0,0,1] neg_hi:[0,0,1]
	v_add_f32_e32 v32, v36, v32
	v_mbcnt_lo_u32_b32 v66, -1, 0
	v_mbcnt_hi_u32_b32 v66, -1, v66
	ds_read_b128 v[36:39], v62
	ds_read_b128 v[40:43], v62 offset:32
	v_pk_mul_f32 v[34:35], v[22:23], v[22:23]
	v_add_f32_e32 v32, v32, v33
	v_add_f32_e32 v32, v32, v34
	v_pk_mul_f32 v[138:139], v[20:21], v[20:21]
	v_add_f32_e32 v32, v32, v35
	v_add_f32_e32 v32, v32, v138
	v_pk_mul_f32 v[136:137], v[18:19], v[18:19]
	v_add_f32_e32 v32, v32, v139
	v_add_f32_e32 v32, v32, v136
	v_pk_mul_f32 v[142:143], v[16:17], v[16:17]
	v_add_f32_e32 v32, v32, v137
	v_add_f32_e32 v32, v32, v142
	v_pk_mul_f32 v[140:141], v[14:15], v[14:15]
	v_add_f32_e32 v32, v32, v143
	v_add_f32_e32 v32, v32, v140
	v_pk_mul_f32 v[44:45], v[12:13], v[12:13]
	v_add_f32_e32 v32, v32, v141
	v_add_f32_e32 v32, v32, v44
	v_pk_mul_f32 v[46:47], v[10:11], v[10:11]
	v_add_f32_e32 v32, v32, v45
	v_add_f32_e32 v32, v32, v46
	v_pk_mul_f32 v[48:49], v[8:9], v[8:9]
	v_add_f32_e32 v32, v32, v47
	v_add_f32_e32 v32, v32, v48
	v_pk_mul_f32 v[50:51], v[6:7], v[6:7]
	v_add_f32_e32 v32, v32, v49
	v_add_f32_e32 v32, v32, v50
	v_pk_mul_f32 v[52:53], v[4:5], v[4:5]
	v_add_f32_e32 v32, v32, v51
	v_add_f32_e32 v32, v32, v52
	v_pk_mul_f32 v[54:55], v[2:3], v[2:3]
	v_add_f32_e32 v32, v32, v53
	v_add_f32_e32 v32, v32, v54
	v_pk_mul_f32 v[56:57], v[0:1], v[0:1]
	v_add_f32_e32 v32, v32, v55
	v_add_f32_e32 v32, v32, v56
	v_add_f32_e32 v32, v32, v57
	v_add_f32_e32 v32, v32, v98
	v_add_f32_e32 v32, v32, v99
	v_add_f32_e32 v32, v32, v100
	v_pk_mul_f32 v[102:103], v[60:61], v[60:61]
	v_add_f32_e32 v32, v32, v101
	v_add_f32_e32 v32, v32, v102
	v_add_f32_e32 v34, v32, v103
	v_lshlrev_b32_e32 v32, 2, v66
	v_xor_b32_e32 v32, 0x80, v32
	ds_bpermute_b32 v35, v32, v34
	v_or_b32_e32 v32, s30, v94
	v_mov_b32_e32 v33, s31
	v_lshlrev_b64 v[32:33], 11, v[32:33]
	v_readlane_b32 s7, v253, 17
	s_waitcnt lgkmcnt(0)
	v_add_f32_e32 v34, v34, v35
	v_fmamk_f32 v34, v34, 0x3c000000, v217
	v_mul_f32_e32 v35, 0x4f800000, v34
	v_cmp_gt_f32_e32 vcc, s79, v34
	v_lshl_add_u64 v[32:33], s[6:7], 0, v[32:33]
	v_lshl_add_u64 v[32:33], s[20:21], 1, v[32:33]
	v_cndmask_b32_e32 v34, v34, v35, vcc
	v_sqrt_f32_e32 v35, v34
	s_nop 0
	v_add_u32_e32 v44, -1, v35
	v_fma_f32 v45, -v44, v35, v34
	v_cmp_ge_f32_e64 s[10:11], 0, v45
	v_add_u32_e32 v45, 1, v35
	s_nop 0
	v_cndmask_b32_e64 v44, v35, v44, s[10:11]
	v_fma_f32 v35, -v45, v35, v34
	v_cmp_lt_f32_e64 s[10:11], 0, v35
	s_nop 1
	v_cndmask_b32_e64 v35, v44, v45, s[10:11]
	v_mul_f32_e32 v44, 0x37800000, v35
	v_cndmask_b32_e32 v35, v35, v44, vcc
	v_cmp_class_f32_e32 vcc, v34, v215
	s_nop 1
	v_cndmask_b32_e32 v44, v35, v34, vcc
	v_div_scale_f32 v45, s[6:7], v44, v44, 1.0
	v_rcp_f32_e32 v46, v45
	v_lshlrev_b32_e32 v34, 3, v67
	v_ashrrev_i32_e32 v35, 31, v34
	v_lshl_add_u64 v[32:33], v[34:35], 1, v[32:33]
	v_fma_f32 v34, -v45, v46, 1.0
	v_fmac_f32_e32 v46, v34, v46
	v_div_scale_f32 v34, vcc, 1.0, v44, 1.0
	v_mul_f32_e32 v35, v34, v46
	v_fma_f32 v47, -v45, v35, v34
	v_fmac_f32_e32 v35, v47, v46
	v_fma_f32 v34, -v45, v35, v34
	v_div_fmas_f32 v34, v34, v46, v35
	v_div_fixup_f32 v34, v34, v44, 1.0
	v_mul_f32_e32 v34, v151, v34
	v_pk_mul_f32 v[44:45], v[92:93], v[34:35] op_sel_hi:[1,0]
	v_pk_mul_f32 v[46:47], v[74:75], v[34:35] op_sel_hi:[1,0]
	s_waitcnt lgkmcnt(1)
	v_pk_mul_f32 v[36:37], v[36:37], v[44:45]
	v_pk_mul_f32 v[44:45], v[90:91], v[34:35] op_sel_hi:[1,0]
	v_cvt_pk_bf16_f32 v36, v36, v37
	v_pk_mul_f32 v[38:39], v[38:39], v[44:45]
	v_pk_mul_f32 v[44:45], v[84:85], v[34:35] op_sel_hi:[1,0]
	v_cvt_pk_bf16_f32 v37, v38, v39
	v_pk_mul_f32 v[38:39], v[88:89], v[34:35] op_sel_hi:[1,0]
	v_pk_mul_f32 v[48:49], v[72:73], v[34:35] op_sel_hi:[1,0]
	s_waitcnt lgkmcnt(0)
	v_pk_mul_f32 v[38:39], v[40:41], v[38:39]
	v_pk_mul_f32 v[40:41], v[86:87], v[34:35] op_sel_hi:[1,0]
	v_cvt_pk_bf16_f32 v38, v38, v39
	v_pk_mul_f32 v[40:41], v[42:43], v[40:41]
	s_nop 0
	v_permlane32_swap_b32_e32 v36, v38
	v_cvt_pk_bf16_f32 v39, v40, v41
	s_nop 1
	v_permlane32_swap_b32_e32 v37, v39
	global_store_dwordx4 v[32:33], v[36:39], off
	s_nop 0
	ds_read_b128 v[36:39], v62 offset:64
	s_nop 0
	ds_read_b128 v[40:43], v62 offset:96
	v_pk_mul_f32 v[50:51], v[70:71], v[34:35] op_sel_hi:[1,0]
	v_pk_mul_f32 v[26:27], v[26:27], v[34:35] op_sel_hi:[1,0]
	v_pk_mul_f32 v[28:29], v[28:29], v[34:35] op_sel_hi:[1,0]
	v_pk_mul_f32 v[30:31], v[30:31], v[34:35] op_sel_hi:[1,0]
	v_pk_mul_f32 v[24:25], v[24:25], v[34:35] op_sel_hi:[1,0]
	v_pk_mul_f32 v[22:23], v[22:23], v[34:35] op_sel_hi:[1,0]
	v_pk_mul_f32 v[20:21], v[20:21], v[34:35] op_sel_hi:[1,0]
	v_pk_mul_f32 v[18:19], v[18:19], v[34:35] op_sel_hi:[1,0]
	v_pk_mul_f32 v[16:17], v[16:17], v[34:35] op_sel_hi:[1,0]
	v_pk_mul_f32 v[14:15], v[14:15], v[34:35] op_sel_hi:[1,0]
	v_pk_mul_f32 v[12:13], v[12:13], v[34:35] op_sel_hi:[1,0]
	v_pk_mul_f32 v[10:11], v[10:11], v[34:35] op_sel_hi:[1,0]
	v_pk_mul_f32 v[8:9], v[8:9], v[34:35] op_sel_hi:[1,0]
	v_pk_mul_f32 v[6:7], v[6:7], v[34:35] op_sel_hi:[1,0]
	v_pk_mul_f32 v[4:5], v[4:5], v[34:35] op_sel_hi:[1,0]
	v_pk_mul_f32 v[2:3], v[2:3], v[34:35] op_sel_hi:[1,0]
	v_pk_mul_f32 v[0:1], v[0:1], v[34:35] op_sel_hi:[1,0]
	s_waitcnt lgkmcnt(1)
	v_pk_mul_f32 v[36:37], v[36:37], v[44:45]
	v_pk_mul_f32 v[44:45], v[82:83], v[34:35] op_sel_hi:[1,0]
	v_cvt_pk_bf16_f32 v36, v36, v37
	v_pk_mul_f32 v[38:39], v[38:39], v[44:45]
	v_pk_mul_f32 v[44:45], v[76:77], v[34:35] op_sel_hi:[1,0]
	v_cvt_pk_bf16_f32 v37, v38, v39
	v_pk_mul_f32 v[38:39], v[80:81], v[34:35] op_sel_hi:[1,0]
	s_waitcnt lgkmcnt(0)
	v_pk_mul_f32 v[38:39], v[40:41], v[38:39]
	v_pk_mul_f32 v[40:41], v[78:79], v[34:35] op_sel_hi:[1,0]
	v_cvt_pk_bf16_f32 v38, v38, v39
	v_pk_mul_f32 v[40:41], v[42:43], v[40:41]
	s_nop 0
	v_permlane32_swap_b32_e32 v36, v38
	v_cvt_pk_bf16_f32 v39, v40, v41
	s_nop 1
	v_permlane32_swap_b32_e32 v37, v39
	global_store_dwordx4 v[32:33], v[36:39], off offset:32
	s_nop 0
	ds_read_b128 v[36:39], v62 offset:128
	s_nop 0
	ds_read_b128 v[40:43], v62 offset:160
	s_waitcnt lgkmcnt(1)
	v_pk_mul_f32 v[36:37], v[44:45], v[36:37]
	v_pk_mul_f32 v[38:39], v[46:47], v[38:39]
	s_waitcnt lgkmcnt(0)
	v_pk_mul_f32 v[40:41], v[48:49], v[40:41]
	v_pk_mul_f32 v[42:43], v[50:51], v[42:43]
	v_cvt_pk_bf16_f32 v36, v36, v37
	v_cvt_pk_bf16_f32 v37, v38, v39
	v_cvt_pk_bf16_f32 v38, v40, v41
	v_cvt_pk_bf16_f32 v39, v42, v43
	s_nop 0
	v_permlane32_swap_b32_e32 v36, v38
	v_permlane32_swap_b32_e32 v37, v39
	global_store_dwordx4 v[32:33], v[36:39], off offset:64
	s_nop 0
	ds_read_b128 v[36:39], v62 offset:192
	s_nop 0
	ds_read_b128 v[40:43], v62 offset:224
	v_pk_mul_f32 v[44:45], v[68:69], v[34:35] op_sel_hi:[1,0]
	s_waitcnt lgkmcnt(1)
	v_pk_mul_f32 v[38:39], v[26:27], v[38:39]
	v_pk_mul_f32 v[36:37], v[44:45], v[36:37]
	s_waitcnt lgkmcnt(0)
	v_pk_mul_f32 v[28:29], v[28:29], v[40:41]
	v_pk_mul_f32 v[30:31], v[30:31], v[42:43]
	v_cvt_pk_bf16_f32 v26, v36, v37
	v_cvt_pk_bf16_f32 v27, v38, v39
	v_cvt_pk_bf16_f32 v28, v28, v29
	v_cvt_pk_bf16_f32 v29, v30, v31
	s_nop 0
	v_permlane32_swap_b32_e32 v26, v28
	v_permlane32_swap_b32_e32 v27, v29
	global_store_dwordx4 v[32:33], v[26:29], off offset:96
	s_nop 0
	ds_read_b128 v[26:29], v62 offset:256
	s_nop 0
	ds_read_b128 v[36:39], v62 offset:288
	s_waitcnt lgkmcnt(1)
	v_pk_mul_f32 v[24:25], v[24:25], v[26:27]
	v_pk_mul_f32 v[22:23], v[22:23], v[28:29]
	s_waitcnt lgkmcnt(0)
	v_pk_mul_f32 v[20:21], v[20:21], v[36:37]
	v_pk_mul_f32 v[26:27], v[18:19], v[38:39]
	v_cvt_pk_bf16_f32 v18, v24, v25
	v_cvt_pk_bf16_f32 v19, v22, v23
	v_cvt_pk_bf16_f32 v20, v20, v21
	v_cvt_pk_bf16_f32 v21, v26, v27
	s_nop 0
	v_permlane32_swap_b32_e32 v18, v20
	v_permlane32_swap_b32_e32 v19, v21
	global_store_dwordx4 v[32:33], v[18:21], off offset:128
	s_nop 0
	ds_read_b128 v[18:21], v62 offset:320
	s_nop 0
	ds_read_b128 v[22:25], v62 offset:352
	s_waitcnt lgkmcnt(1)
	v_pk_mul_f32 v[16:17], v[16:17], v[18:19]
	v_pk_mul_f32 v[14:15], v[14:15], v[20:21]
	s_waitcnt lgkmcnt(0)
	v_pk_mul_f32 v[12:13], v[12:13], v[22:23]
	v_pk_mul_f32 v[18:19], v[10:11], v[24:25]
	v_cvt_pk_bf16_f32 v10, v16, v17
	v_cvt_pk_bf16_f32 v11, v14, v15
	v_cvt_pk_bf16_f32 v12, v12, v13
	v_cvt_pk_bf16_f32 v13, v18, v19
	s_nop 0
	v_permlane32_swap_b32_e32 v10, v12
	v_permlane32_swap_b32_e32 v11, v13
	global_store_dwordx4 v[32:33], v[10:13], off offset:160
	s_nop 0
	ds_read_b128 v[10:13], v62 offset:384
	s_nop 0
	ds_read_b128 v[14:17], v62 offset:416
	s_waitcnt lgkmcnt(1)
	v_pk_mul_f32 v[8:9], v[8:9], v[10:11]
	v_pk_mul_f32 v[6:7], v[6:7], v[12:13]
	s_waitcnt lgkmcnt(0)
	v_pk_mul_f32 v[4:5], v[4:5], v[14:15]
	v_pk_mul_f32 v[10:11], v[2:3], v[16:17]
	v_cvt_pk_bf16_f32 v2, v8, v9
	v_cvt_pk_bf16_f32 v3, v6, v7
	v_cvt_pk_bf16_f32 v4, v4, v5
	v_cvt_pk_bf16_f32 v5, v10, v11
	s_nop 0
	v_permlane32_swap_b32_e32 v2, v4
	v_permlane32_swap_b32_e32 v3, v5
	global_store_dwordx4 v[32:33], v[2:5], off offset:192
	s_nop 0
	ds_read_b128 v[2:5], v62 offset:448
	s_nop 0
	ds_read_b128 v[6:9], v62 offset:480
	v_pk_mul_f32 v[10:11], v[58:59], v[34:35] op_sel_hi:[1,0]
	v_pk_mul_f32 v[12:13], v[64:65], v[34:35] op_sel_hi:[1,0]
	v_pk_mul_f32 v[14:15], v[60:61], v[34:35] op_sel_hi:[1,0]
	s_waitcnt lgkmcnt(1)
	v_pk_mul_f32 v[0:1], v[0:1], v[2:3]
	v_pk_mul_f32 v[2:3], v[10:11], v[4:5]
	s_waitcnt lgkmcnt(0)
	v_pk_mul_f32 v[4:5], v[12:13], v[6:7]
	v_pk_mul_f32 v[6:7], v[14:15], v[8:9]
	v_cvt_pk_bf16_f32 v0, v0, v1
	v_cvt_pk_bf16_f32 v1, v2, v3
	v_cvt_pk_bf16_f32 v2, v4, v5
	v_cvt_pk_bf16_f32 v3, v6, v7
	s_nop 0
	v_permlane32_swap_b32_e32 v0, v2
	v_permlane32_swap_b32_e32 v1, v3
	global_store_dwordx4 v[32:33], v[0:3], off offset:224
	s_branch .LBB0_256
.Lda_pop_b:
	s_cmp_eq_u32 s95, 0x100
	s_cbranch_scc0 .Lda_popskip_b
	s_mov_b64 exec, 1
	global_atomic_add v0, v231, v214, s[16:17] sc0
	s_waitcnt vmcnt(0)
	s_movk_i32 s3, 0x7f
	v_cmp_lt_u32_e32 vcc, s3, v0
	s_and_saveexec_b64 s[12:13], vcc
	s_cbranch_execz .Lda_popw_b
	global_atomic_add v0, v231, v214, s[18:19] sc0
	s_waitcnt vmcnt(0)
	v_or_b32_e32 v1, 0x100, v0
	v_cmp_gt_u32_e32 vcc, s58, v0
	s_nop 1
	v_cndmask_b32_e32 v0, v218, v1, vcc
